# v2_final
# baseline (speedup 1.0000x reference)
.LBB0_1012:
	s_cmp_lt_i32 s96, 11
	s_cselect_b64 s[2:3], -1, 0
	s_and_b64 s[0:1], s[2:3], s[0:1]
	s_and_b64 s[0:1], s[0:1], s[10:11]
	s_andn2_b64 vcc, exec, s[0:1]
	s_cbranch_vccnz .LBB0_1017
	v_mbcnt_hi_u32_b32 v2, -1, v192
	v_and_b32_e32 v3, 64, v2
	v_add_u32_e32 v3, 64, v3
	v_xor_b32_e32 v4, 1, v2
	v_cmp_lt_i32_e32 vcc, v4, v3
	v_mov_b32_e32 v175, 0
	v_lshl_add_u64 v[0:1], s[58:59], 0, v[174:175]
	v_cndmask_b32_e32 v4, v2, v4, vcc
	v_lshlrev_b32_e32 v26, 2, v4
	v_xor_b32_e32 v4, 2, v2
	v_cmp_lt_i32_e32 vcc, v4, v3
	s_mov_b64 s[0:1], 0x314000
	v_mov_b32_e32 v179, v175
	v_cndmask_b32_e32 v4, v2, v4, vcc
	v_lshlrev_b32_e32 v27, 2, v4
	v_xor_b32_e32 v4, 4, v2
	v_cmp_lt_i32_e32 vcc, v4, v3
	v_lshl_add_u64 v[0:1], v[0:1], 0, s[0:1]
	s_mov_b64 s[0:1], 0x33114000
	v_cndmask_b32_e32 v4, v2, v4, vcc
	v_lshlrev_b32_e32 v28, 2, v4
	v_xor_b32_e32 v4, 8, v2
	v_cmp_lt_i32_e32 vcc, v4, v3
	v_mov_b32_e32 v177, v175
	v_lshl_add_u64 v[6:7], s[54:55], 0, v[176:177]
	v_cndmask_b32_e32 v4, v2, v4, vcc
	v_lshlrev_b32_e32 v29, 2, v4
	v_xor_b32_e32 v4, 16, v2
	v_cmp_lt_i32_e32 vcc, v4, v3
	v_lshl_add_u64 v[8:9], s[56:57], 0, v[176:177]
	v_mov_b32_e32 v32, 0x358637bd
	v_cndmask_b32_e32 v4, v2, v4, vcc
	v_lshlrev_b32_e32 v30, 2, v4
	v_xor_b32_e32 v4, 32, v2
	v_cmp_lt_i32_e32 vcc, v4, v3
	s_mov_b32 s4, 0x800000
	s_movk_i32 s5, 0x1000
	v_cndmask_b32_e32 v2, v2, v4, vcc
	s_waitcnt lgkmcnt(0)
	v_lshl_add_u64 v[4:5], s[58:59], 0, v[178:179]
	v_lshlrev_b32_e32 v31, 2, v2
	v_lshl_add_u64 v[2:3], v[4:5], 0, s[0:1]
	s_mov_b64 s[0:1], 0x2b114000
	v_lshl_add_u64 v[4:5], v[4:5], 0, s[0:1]
	s_mov_b64 s[0:1], 0x1000
	s_mov_b64 s[8:9], 0x2000
	s_mov_b64 s[12:13], 0x3000
	v_lshl_add_u64 v[2:3], v[2:3], 0, s[0:1]
	v_lshl_add_u64 v[4:5], v[4:5], 0, s[0:1]
	v_lshl_add_u64 v[8:9], v[8:9], 0, s[0:1]
	v_lshl_add_u64 v[36:37], v[6:7], 0, s[0:1]
	v_lshl_add_u64 v[38:39], v[6:7], 0, s[12:13]
	s_ashr_i32 s35, s34, 31
	v_lshl_add_u64 v[10:11], s[34:35], 2, v[0:1]
	global_load_dword v33, v[10:11], off
	s_waitcnt vmcnt(0)
	ds_bpermute_b32 v11, v26, v33
	s_waitcnt lgkmcnt(0)
	v_add_f32_e32 v10, v33, v11
	ds_bpermute_b32 v11, v27, v10
	s_waitcnt lgkmcnt(0)
	v_add_f32_e32 v10, v10, v11
	ds_bpermute_b32 v11, v28, v10
	s_waitcnt lgkmcnt(0)
	v_add_f32_e32 v10, v10, v11
	ds_bpermute_b32 v11, v29, v10
	s_waitcnt lgkmcnt(0)
	v_add_f32_e32 v10, v10, v11
	ds_bpermute_b32 v11, v30, v10
	s_waitcnt lgkmcnt(0)
	v_add_f32_e32 v10, v10, v11
	ds_bpermute_b32 v11, v31, v10
	s_waitcnt lgkmcnt(0)
	v_add_f32_e32 v10, v10, v11
	v_fmamk_f32 v14, v10, 0x39800000, v32
	v_mul_f32_e32 v15, 0x4b800000, v14
	v_cmp_gt_f32_e32 vcc, s4, v14
	s_nop 1
	v_cndmask_b32_e32 v14, v14, v15, vcc
	v_rsq_f32_e32 v18, v14
	s_nop 0
	v_mul_f32_e32 v19, 0x45800000, v18
	v_cndmask_b32_e32 v18, v18, v19, vcc
	v_mov_b32_e32 v19, v18
.Lfin_row:
	s_ashr_i32 s35, s34, 31
	s_lshl_b64 s[2:3], s[34:35], 13
	s_lshl_b64 s[6:7], s[34:35], 14
	s_add_i32 s10, s34, s60
	s_min_i32 s10, s10, 0x1fff
	s_ashr_i32 s11, s10, 31
	v_lshl_add_u64 v[10:11], s[10:11], 2, v[0:1]
	v_lshl_add_u64 v[12:13], v[2:3], 0, s[2:3]
	v_lshl_add_u64 v[14:15], v[4:5], 0, s[2:3]
	v_lshl_add_u64 v[16:17], v[8:9], 0, s[6:7]
	global_load_dword v33, v[10:11], off
	v_lshl_add_u64 v[22:23], v[16:17], 0, s[8:9]
	global_load_dwordx2 v[64:65], v[12:13], off offset:-4096
	global_load_dwordx2 v[96:97], v[14:15], off offset:-4096
	global_load_dwordx4 v[128:131], v[36:37], off offset:-4096
	global_load_dwordx2 v[66:67], v[12:13], off offset:-3584
	global_load_dwordx2 v[98:99], v[14:15], off offset:-3584
	global_load_dwordx4 v[132:135], v[36:37], off offset:-3072
	global_load_dwordx2 v[68:69], v[12:13], off offset:-3072
	global_load_dwordx2 v[100:101], v[14:15], off offset:-3072
	global_load_dwordx4 v[136:139], v[36:37], off offset:-2048
	global_load_dwordx2 v[70:71], v[12:13], off offset:-2560
	global_load_dwordx2 v[102:103], v[14:15], off offset:-2560
	global_load_dwordx4 v[140:143], v[36:37], off offset:-1024
	global_load_dwordx2 v[72:73], v[12:13], off offset:-2048
	global_load_dwordx2 v[104:105], v[14:15], off offset:-2048
	global_load_dwordx4 v[144:147], v[36:37], off
	global_load_dwordx2 v[74:75], v[12:13], off offset:-1536
	global_load_dwordx2 v[106:107], v[14:15], off offset:-1536
	global_load_dwordx4 v[148:151], v[36:37], off offset:1024
	global_load_dwordx2 v[76:77], v[12:13], off offset:-1024
	global_load_dwordx2 v[108:109], v[14:15], off offset:-1024
	global_load_dwordx4 v[152:155], v[36:37], off offset:2048
	global_load_dwordx2 v[78:79], v[12:13], off offset:-512
	global_load_dwordx2 v[110:111], v[14:15], off offset:-512
	global_load_dwordx4 v[156:159], v[36:37], off offset:3072
	global_load_dwordx2 v[80:81], v[12:13], off
	global_load_dwordx2 v[112:113], v[14:15], off
	global_load_dwordx4 v[160:163], v[38:39], off offset:-4096
	global_load_dwordx2 v[82:83], v[12:13], off offset:512
	global_load_dwordx2 v[114:115], v[14:15], off offset:512
	global_load_dwordx4 v[164:167], v[38:39], off offset:-3072
	global_load_dwordx2 v[84:85], v[12:13], off offset:1024
	global_load_dwordx2 v[116:117], v[14:15], off offset:1024
	global_load_dwordx4 v[168:171], v[38:39], off offset:-2048
	global_load_dwordx2 v[86:87], v[12:13], off offset:1536
	global_load_dwordx2 v[118:119], v[14:15], off offset:1536
	global_load_dwordx4 v[172:175], v[38:39], off offset:-1024
	global_load_dwordx2 v[88:89], v[12:13], off offset:2048
	global_load_dwordx2 v[120:121], v[14:15], off offset:2048
	global_load_dwordx4 v[176:179], v[38:39], off
	global_load_dwordx2 v[90:91], v[12:13], off offset:2560
	global_load_dwordx2 v[122:123], v[14:15], off offset:2560
	global_load_dwordx4 v[180:183], v[38:39], off offset:1024
	global_load_dwordx2 v[92:93], v[12:13], off offset:3072
	global_load_dwordx2 v[124:125], v[14:15], off offset:3072
	global_load_dwordx4 v[184:187], v[38:39], off offset:2048
	global_load_dwordx2 v[94:95], v[12:13], off offset:3584
	global_load_dwordx2 v[126:127], v[14:15], off offset:3584
	global_load_dwordx4 v[188:191], v[38:39], off offset:3072
	s_waitcnt vmcnt(45)
	v_lshlrev_b32_e32 v40, 16, v64
	v_and_b32_e32 v41, 0xffff0000, v64
	v_lshlrev_b32_e32 v42, 16, v65
	v_and_b32_e32 v43, 0xffff0000, v65
	v_lshlrev_b32_e32 v44, 16, v96
	v_and_b32_e32 v45, 0xffff0000, v96
	v_lshlrev_b32_e32 v46, 16, v97
	v_and_b32_e32 v47, 0xffff0000, v97
	v_pk_mul_f32 v[40:41], v[18:19], v[40:41]
	v_pk_mul_f32 v[42:43], v[18:19], v[42:43]
	v_pk_fma_f32 v[128:129], v[128:129], v[40:41], v[44:45]
	v_pk_fma_f32 v[130:131], v[130:131], v[42:43], v[46:47]
	global_store_dwordx4 v[16:17], v[128:131], off offset:-4096
	s_waitcnt vmcnt(43)
	v_lshlrev_b32_e32 v48, 16, v66
	v_and_b32_e32 v49, 0xffff0000, v66
	v_lshlrev_b32_e32 v50, 16, v67
	v_and_b32_e32 v51, 0xffff0000, v67
	v_lshlrev_b32_e32 v52, 16, v98
	v_and_b32_e32 v53, 0xffff0000, v98
	v_lshlrev_b32_e32 v54, 16, v99
	v_and_b32_e32 v55, 0xffff0000, v99
	v_pk_mul_f32 v[48:49], v[18:19], v[48:49]
	v_pk_mul_f32 v[50:51], v[18:19], v[50:51]
	v_pk_fma_f32 v[132:133], v[132:133], v[48:49], v[52:53]
	v_pk_fma_f32 v[134:135], v[134:135], v[50:51], v[54:55]
	global_store_dwordx4 v[16:17], v[132:135], off offset:-3072
	s_waitcnt vmcnt(41)
	v_lshlrev_b32_e32 v40, 16, v68
	v_and_b32_e32 v41, 0xffff0000, v68
	v_lshlrev_b32_e32 v42, 16, v69
	v_and_b32_e32 v43, 0xffff0000, v69
	v_lshlrev_b32_e32 v44, 16, v100
	v_and_b32_e32 v45, 0xffff0000, v100
	v_lshlrev_b32_e32 v46, 16, v101
	v_and_b32_e32 v47, 0xffff0000, v101
	v_pk_mul_f32 v[40:41], v[18:19], v[40:41]
	v_pk_mul_f32 v[42:43], v[18:19], v[42:43]
	v_pk_fma_f32 v[136:137], v[136:137], v[40:41], v[44:45]
	v_pk_fma_f32 v[138:139], v[138:139], v[42:43], v[46:47]
	global_store_dwordx4 v[16:17], v[136:139], off offset:-2048
	s_waitcnt vmcnt(39)
	v_lshlrev_b32_e32 v48, 16, v70
	v_and_b32_e32 v49, 0xffff0000, v70
	v_lshlrev_b32_e32 v50, 16, v71
	v_and_b32_e32 v51, 0xffff0000, v71
	v_lshlrev_b32_e32 v52, 16, v102
	v_and_b32_e32 v53, 0xffff0000, v102
	v_lshlrev_b32_e32 v54, 16, v103
	v_and_b32_e32 v55, 0xffff0000, v103
	v_pk_mul_f32 v[48:49], v[18:19], v[48:49]
	v_pk_mul_f32 v[50:51], v[18:19], v[50:51]
	v_pk_fma_f32 v[140:141], v[140:141], v[48:49], v[52:53]
	v_pk_fma_f32 v[142:143], v[142:143], v[50:51], v[54:55]
	global_store_dwordx4 v[16:17], v[140:143], off offset:-1024
	s_waitcnt vmcnt(37)
	v_lshlrev_b32_e32 v40, 16, v72
	v_and_b32_e32 v41, 0xffff0000, v72
	v_lshlrev_b32_e32 v42, 16, v73
	v_and_b32_e32 v43, 0xffff0000, v73
	v_lshlrev_b32_e32 v44, 16, v104
	v_and_b32_e32 v45, 0xffff0000, v104
	v_lshlrev_b32_e32 v46, 16, v105
	v_and_b32_e32 v47, 0xffff0000, v105
	v_pk_mul_f32 v[40:41], v[18:19], v[40:41]
	v_pk_mul_f32 v[42:43], v[18:19], v[42:43]
	v_pk_fma_f32 v[144:145], v[144:145], v[40:41], v[44:45]
	v_pk_fma_f32 v[146:147], v[146:147], v[42:43], v[46:47]
	global_store_dwordx4 v[16:17], v[144:147], off
	s_waitcnt vmcnt(35)
	v_lshlrev_b32_e32 v48, 16, v74
	v_and_b32_e32 v49, 0xffff0000, v74
	v_lshlrev_b32_e32 v50, 16, v75
	v_and_b32_e32 v51, 0xffff0000, v75
	v_lshlrev_b32_e32 v52, 16, v106
	v_and_b32_e32 v53, 0xffff0000, v106
	v_lshlrev_b32_e32 v54, 16, v107
	v_and_b32_e32 v55, 0xffff0000, v107
	v_pk_mul_f32 v[48:49], v[18:19], v[48:49]
	v_pk_mul_f32 v[50:51], v[18:19], v[50:51]
	v_pk_fma_f32 v[148:149], v[148:149], v[48:49], v[52:53]
	v_pk_fma_f32 v[150:151], v[150:151], v[50:51], v[54:55]
	global_store_dwordx4 v[16:17], v[148:151], off offset:1024
	s_waitcnt vmcnt(33)
	v_lshlrev_b32_e32 v40, 16, v76
	v_and_b32_e32 v41, 0xffff0000, v76
	v_lshlrev_b32_e32 v42, 16, v77
	v_and_b32_e32 v43, 0xffff0000, v77
	v_lshlrev_b32_e32 v44, 16, v108
	v_and_b32_e32 v45, 0xffff0000, v108
	v_lshlrev_b32_e32 v46, 16, v109
	v_and_b32_e32 v47, 0xffff0000, v109
	v_pk_mul_f32 v[40:41], v[18:19], v[40:41]
	v_pk_mul_f32 v[42:43], v[18:19], v[42:43]
	v_pk_fma_f32 v[152:153], v[152:153], v[40:41], v[44:45]
	v_pk_fma_f32 v[154:155], v[154:155], v[42:43], v[46:47]
	global_store_dwordx4 v[16:17], v[152:155], off offset:2048
	s_waitcnt vmcnt(31)
	v_lshlrev_b32_e32 v48, 16, v78
	v_and_b32_e32 v49, 0xffff0000, v78
	v_lshlrev_b32_e32 v50, 16, v79
	v_and_b32_e32 v51, 0xffff0000, v79
	v_lshlrev_b32_e32 v52, 16, v110
	v_and_b32_e32 v53, 0xffff0000, v110
	v_lshlrev_b32_e32 v54, 16, v111
	v_and_b32_e32 v55, 0xffff0000, v111
	v_pk_mul_f32 v[48:49], v[18:19], v[48:49]
	v_pk_mul_f32 v[50:51], v[18:19], v[50:51]
	v_pk_fma_f32 v[156:157], v[156:157], v[48:49], v[52:53]
	v_pk_fma_f32 v[158:159], v[158:159], v[50:51], v[54:55]
	global_store_dwordx4 v[16:17], v[156:159], off offset:3072
	s_waitcnt vmcnt(29)
	v_lshlrev_b32_e32 v40, 16, v80
	v_and_b32_e32 v41, 0xffff0000, v80
	v_lshlrev_b32_e32 v42, 16, v81
	v_and_b32_e32 v43, 0xffff0000, v81
	v_lshlrev_b32_e32 v44, 16, v112
	v_and_b32_e32 v45, 0xffff0000, v112
	v_lshlrev_b32_e32 v46, 16, v113
	v_and_b32_e32 v47, 0xffff0000, v113
	v_pk_mul_f32 v[40:41], v[18:19], v[40:41]
	v_pk_mul_f32 v[42:43], v[18:19], v[42:43]
	v_pk_fma_f32 v[160:161], v[160:161], v[40:41], v[44:45]
	v_pk_fma_f32 v[162:163], v[162:163], v[42:43], v[46:47]
	global_store_dwordx4 v[22:23], v[160:163], off offset:-4096
	s_waitcnt vmcnt(27)
	v_lshlrev_b32_e32 v48, 16, v82
	v_and_b32_e32 v49, 0xffff0000, v82
	v_lshlrev_b32_e32 v50, 16, v83
	v_and_b32_e32 v51, 0xffff0000, v83
	v_lshlrev_b32_e32 v52, 16, v114
	v_and_b32_e32 v53, 0xffff0000, v114
	v_lshlrev_b32_e32 v54, 16, v115
	v_and_b32_e32 v55, 0xffff0000, v115
	v_pk_mul_f32 v[48:49], v[18:19], v[48:49]
	v_pk_mul_f32 v[50:51], v[18:19], v[50:51]
	v_pk_fma_f32 v[164:165], v[164:165], v[48:49], v[52:53]
	v_pk_fma_f32 v[166:167], v[166:167], v[50:51], v[54:55]
	global_store_dwordx4 v[22:23], v[164:167], off offset:-3072
	s_waitcnt vmcnt(25)
	v_lshlrev_b32_e32 v40, 16, v84
	v_and_b32_e32 v41, 0xffff0000, v84
	v_lshlrev_b32_e32 v42, 16, v85
	v_and_b32_e32 v43, 0xffff0000, v85
	v_lshlrev_b32_e32 v44, 16, v116
	v_and_b32_e32 v45, 0xffff0000, v116
	v_lshlrev_b32_e32 v46, 16, v117
	v_and_b32_e32 v47, 0xffff0000, v117
	v_pk_mul_f32 v[40:41], v[18:19], v[40:41]
	v_pk_mul_f32 v[42:43], v[18:19], v[42:43]
	v_pk_fma_f32 v[168:169], v[168:169], v[40:41], v[44:45]
	v_pk_fma_f32 v[170:171], v[170:171], v[42:43], v[46:47]
	global_store_dwordx4 v[22:23], v[168:171], off offset:-2048
	s_waitcnt vmcnt(23)
	v_lshlrev_b32_e32 v48, 16, v86
	v_and_b32_e32 v49, 0xffff0000, v86
	v_lshlrev_b32_e32 v50, 16, v87
	v_and_b32_e32 v51, 0xffff0000, v87
	v_lshlrev_b32_e32 v52, 16, v118
	v_and_b32_e32 v53, 0xffff0000, v118
	v_lshlrev_b32_e32 v54, 16, v119
	v_and_b32_e32 v55, 0xffff0000, v119
	v_pk_mul_f32 v[48:49], v[18:19], v[48:49]
	v_pk_mul_f32 v[50:51], v[18:19], v[50:51]
	v_pk_fma_f32 v[172:173], v[172:173], v[48:49], v[52:53]
	v_pk_fma_f32 v[174:175], v[174:175], v[50:51], v[54:55]
	global_store_dwordx4 v[22:23], v[172:175], off offset:-1024
	s_waitcnt vmcnt(21)
	v_lshlrev_b32_e32 v40, 16, v88
	v_and_b32_e32 v41, 0xffff0000, v88
	v_lshlrev_b32_e32 v42, 16, v89
	v_and_b32_e32 v43, 0xffff0000, v89
	v_lshlrev_b32_e32 v44, 16, v120
	v_and_b32_e32 v45, 0xffff0000, v120
	v_lshlrev_b32_e32 v46, 16, v121
	v_and_b32_e32 v47, 0xffff0000, v121
	v_pk_mul_f32 v[40:41], v[18:19], v[40:41]
	v_pk_mul_f32 v[42:43], v[18:19], v[42:43]
	v_pk_fma_f32 v[176:177], v[176:177], v[40:41], v[44:45]
	v_pk_fma_f32 v[178:179], v[178:179], v[42:43], v[46:47]
	global_store_dwordx4 v[22:23], v[176:179], off
	s_waitcnt vmcnt(19)
	v_lshlrev_b32_e32 v48, 16, v90
	v_and_b32_e32 v49, 0xffff0000, v90
	v_lshlrev_b32_e32 v50, 16, v91
	v_and_b32_e32 v51, 0xffff0000, v91
	v_lshlrev_b32_e32 v52, 16, v122
	v_and_b32_e32 v53, 0xffff0000, v122
	v_lshlrev_b32_e32 v54, 16, v123
	v_and_b32_e32 v55, 0xffff0000, v123
	v_pk_mul_f32 v[48:49], v[18:19], v[48:49]
	v_pk_mul_f32 v[50:51], v[18:19], v[50:51]
	v_pk_fma_f32 v[180:181], v[180:181], v[48:49], v[52:53]
	v_pk_fma_f32 v[182:183], v[182:183], v[50:51], v[54:55]
	global_store_dwordx4 v[22:23], v[180:183], off offset:1024
	s_waitcnt vmcnt(17)
	v_lshlrev_b32_e32 v40, 16, v92
	v_and_b32_e32 v41, 0xffff0000, v92
	v_lshlrev_b32_e32 v42, 16, v93
	v_and_b32_e32 v43, 0xffff0000, v93
	v_lshlrev_b32_e32 v44, 16, v124
	v_and_b32_e32 v45, 0xffff0000, v124
	v_lshlrev_b32_e32 v46, 16, v125
	v_and_b32_e32 v47, 0xffff0000, v125
	v_pk_mul_f32 v[40:41], v[18:19], v[40:41]
	v_pk_mul_f32 v[42:43], v[18:19], v[42:43]
	v_pk_fma_f32 v[184:185], v[184:185], v[40:41], v[44:45]
	v_pk_fma_f32 v[186:187], v[186:187], v[42:43], v[46:47]
	global_store_dwordx4 v[22:23], v[184:187], off offset:2048
	s_waitcnt vmcnt(15)
	v_lshlrev_b32_e32 v48, 16, v94
	v_and_b32_e32 v49, 0xffff0000, v94
	v_lshlrev_b32_e32 v50, 16, v95
	v_and_b32_e32 v51, 0xffff0000, v95
	v_lshlrev_b32_e32 v52, 16, v126
	v_and_b32_e32 v53, 0xffff0000, v126
	v_lshlrev_b32_e32 v54, 16, v127
	v_and_b32_e32 v55, 0xffff0000, v127
	v_pk_mul_f32 v[48:49], v[18:19], v[48:49]
	v_pk_mul_f32 v[50:51], v[18:19], v[50:51]
	v_pk_fma_f32 v[188:189], v[188:189], v[48:49], v[52:53]
	v_pk_fma_f32 v[190:191], v[190:191], v[50:51], v[54:55]
	global_store_dwordx4 v[22:23], v[188:191], off offset:3072
	ds_bpermute_b32 v11, v26, v33
	s_waitcnt lgkmcnt(0)
	v_add_f32_e32 v10, v33, v11
	ds_bpermute_b32 v11, v27, v10
	s_waitcnt lgkmcnt(0)
	v_add_f32_e32 v10, v10, v11
	ds_bpermute_b32 v11, v28, v10
	s_waitcnt lgkmcnt(0)
	v_add_f32_e32 v10, v10, v11
	ds_bpermute_b32 v11, v29, v10
	s_waitcnt lgkmcnt(0)
	v_add_f32_e32 v10, v10, v11
	ds_bpermute_b32 v11, v30, v10
	s_waitcnt lgkmcnt(0)
	v_add_f32_e32 v10, v10, v11
	ds_bpermute_b32 v11, v31, v10
	s_waitcnt lgkmcnt(0)
	v_add_f32_e32 v10, v10, v11
	v_fmamk_f32 v14, v10, 0x39800000, v32
	v_mul_f32_e32 v15, 0x4b800000, v14
	v_cmp_gt_f32_e32 vcc, s4, v14
	s_nop 1
	v_cndmask_b32_e32 v14, v14, v15, vcc
	v_rsq_f32_e32 v18, v14
	s_nop 0
	v_mul_f32_e32 v19, 0x45800000, v18
	v_cndmask_b32_e32 v18, v18, v19, vcc
	v_mov_b32_e32 v19, v18
	s_add_i32 s34, s34, s60
	s_cmpk_gt_i32 s34, 0x1fff
	s_cbranch_scc0 .Lfin_row
